# seam 9 (P9 to P10) also a group barrier; the weight conversions done inside seams are tracked by sharded per-workgroup counters that seam 9 waits for
# speedup vs baseline: 1.0141x; 1.0049x over previous
.LBB0_356:
	s_or_b64 exec, exec, s[4:5]
	s_waitcnt lgkmcnt(0)
	s_barrier
	v_readlane_b32 s6, v254, 7
	v_readlane_b32 s7, v254, 8
	s_and_saveexec_b64 s[10:11], s[6:7]
	s_cbranch_execz .Lmy_cnt2
	s_and_b32 s6, s2, 15
	s_lshl_b32 s6, s6, 8
	s_add_u32 s6, s6, 0x35000
	v_mov_b32_e32 v2, s6
	v_mov_b32_e32 v3, 1
	global_atomic_add v2, v3, s[50:51]
.Lmy_cnt2:
	s_mov_b64 exec, s[10:11]

.LBB0_921:
	global_load_dwordx4 v[36:39], v[34:35], off nt
	global_load_dwordx4 v[40:43], v[34:35], off offset:1024 nt
	global_load_dwordx4 v[56:59], v[34:35], off offset:2048 nt
	global_load_dwordx4 v[60:63], v[34:35], off offset:3072 nt
	s_ashr_i32 s6, s98, 12
	s_mul_hi_i32 s7, s6, 0x12000
	s_mul_i32 s6, s6, 0x12000
	s_add_u32 s8, s50, s6
	s_addc_u32 s9, s51, s7
	s_add_u32 s6, s8, 0xc000
	s_addc_u32 s7, s9, 0
	s_add_u32 s8, s8, 0xe000
	s_addc_u32 s9, s9, 0
	global_load_dwordx4 v[64:67], v51, s[6:7] offset:16
	global_load_dwordx4 v[68:71], v51, s[6:7]
	global_load_dwordx4 v[72:75], v51, s[8:9] offset:16
	global_load_dwordx4 v[76:79], v51, s[8:9]
	v_add_co_u32_e32 v80, vcc, s10, v34
	s_add_i32 s98, s98, s101
	s_nop 0
	v_addc_co_u32_e32 v81, vcc, -1, v35, vcc
	s_cmp_lt_i32 s98, s100
	s_waitcnt vmcnt(0)
	v_cvt_f32_f16_sdwa v83, v36 dst_sel:DWORD dst_unused:UNUSED_PAD src0_sel:WORD_1
	v_cvt_f32_f16_sdwa v85, v37 dst_sel:DWORD dst_unused:UNUSED_PAD src0_sel:WORD_1
	v_cvt_f32_f16_sdwa v87, v38 dst_sel:DWORD dst_unused:UNUSED_PAD src0_sel:WORD_1
	v_cvt_f32_f16_sdwa v89, v39 dst_sel:DWORD dst_unused:UNUSED_PAD src0_sel:WORD_1
	v_cvt_f32_f16_e32 v82, v36
	v_cvt_f32_f16_e32 v84, v37
	v_cvt_f32_f16_e32 v86, v38
	v_cvt_f32_f16_e32 v88, v39
	v_cvt_f32_f16_sdwa v91, v40 dst_sel:DWORD dst_unused:UNUSED_PAD src0_sel:WORD_1
	v_cvt_f32_f16_sdwa v93, v41 dst_sel:DWORD dst_unused:UNUSED_PAD src0_sel:WORD_1
	v_cvt_f32_f16_e32 v90, v40
	v_cvt_f32_f16_e32 v92, v41
	v_cvt_f32_f16_e32 v94, v42
	v_cvt_f32_f16_e32 v96, v43
	v_cvt_f32_f16_sdwa v95, v42 dst_sel:DWORD dst_unused:UNUSED_PAD src0_sel:WORD_1
	v_cvt_f32_f16_sdwa v97, v43 dst_sel:DWORD dst_unused:UNUSED_PAD src0_sel:WORD_1
	v_cvt_f32_f16_sdwa v99, v56 dst_sel:DWORD dst_unused:UNUSED_PAD src0_sel:WORD_1
	v_cvt_f32_f16_e32 v98, v56
	v_cvt_f32_f16_sdwa v101, v57 dst_sel:DWORD dst_unused:UNUSED_PAD src0_sel:WORD_1
	v_cvt_f32_f16_e32 v100, v57
	v_cvt_f32_f16_sdwa v103, v58 dst_sel:DWORD dst_unused:UNUSED_PAD src0_sel:WORD_1
	v_cvt_f32_f16_e32 v102, v58
	v_cvt_f32_f16_sdwa v105, v59 dst_sel:DWORD dst_unused:UNUSED_PAD src0_sel:WORD_1
	v_cvt_f32_f16_e32 v104, v59
	v_cvt_f32_f16_sdwa v39, v62 dst_sel:DWORD dst_unused:UNUSED_PAD src0_sel:WORD_1
	v_cvt_f32_f16_e32 v38, v62
	v_cvt_f32_f16_sdwa v43, v63 dst_sel:DWORD dst_unused:UNUSED_PAD src0_sel:WORD_1
	v_cvt_f32_f16_e32 v42, v63
	v_mov_b32_e32 v58, v83
	v_mov_b32_e32 v59, v87
	v_mov_b32_e32 v62, v85
	v_mov_b32_e32 v63, v89
	v_cvt_f32_f16_sdwa v37, v60 dst_sel:DWORD dst_unused:UNUSED_PAD src0_sel:WORD_1
	v_cvt_f32_f16_e32 v36, v60
	v_cvt_f32_f16_sdwa v41, v61 dst_sel:DWORD dst_unused:UNUSED_PAD src0_sel:WORD_1
	v_cvt_f32_f16_e32 v40, v61
	v_mov_b32_e32 v56, v82
	v_mov_b32_e32 v57, v86
	v_mov_b32_e32 v60, v84
	v_mov_b32_e32 v61, v88
	v_mov_b32_e32 v108, v91
	v_mov_b32_e32 v109, v93
	v_pk_mul_f32 v[58:59], v[58:59], v[58:59]
	v_pk_mul_f32 v[62:63], v[62:63], v[62:63]
	v_mov_b32_e32 v106, v90
	v_mov_b32_e32 v107, v92
	v_pk_mul_f32 v[108:109], v[108:109], v[108:109]
	v_pk_fma_f32 v[56:57], v[56:57], v[56:57], v[58:59]
	v_pk_fma_f32 v[58:59], v[60:61], v[60:61], v[62:63]
	v_mul_f32_e32 v110, v94, v94
	v_mul_f32_e32 v112, v96, v96
	v_pk_fma_f32 v[60:61], v[106:107], v[106:107], v[108:109]
	v_pk_add_f32 v[56:57], v[56:57], v[58:59]
	v_pk_mul_f32 v[114:115], v[98:99], v[98:99]
	v_pk_mul_f32 v[116:117], v[100:101], v[100:101]
	v_pk_fma_f32 v[110:111], v[94:95], v[94:95], v[110:111] op_sel_hi:[1,1,0]
	v_pk_fma_f32 v[112:113], v[96:97], v[96:97], v[112:113] op_sel_hi:[1,1,0]
	v_pk_add_f32 v[58:59], v[60:61], v[60:61] op_sel_hi:[0,1]
	v_pk_add_f32 v[56:57], v[56:57], v[56:57] op_sel_hi:[0,1]
	v_mov_b32_e32 v120, v103
	v_mov_b32_e32 v121, v105
	v_mov_b32_e32 v110, v114
	v_mov_b32_e32 v112, v115
	v_mov_b32_e32 v58, v117
	v_mov_b32_e32 v56, v116
	v_mov_b32_e32 v118, v102
	v_mov_b32_e32 v119, v104
	v_pk_mul_f32 v[120:121], v[120:121], v[120:121]
	v_pk_add_f32 v[60:61], v[110:111], v[112:113]
	v_pk_add_f32 v[56:57], v[56:57], v[58:59]
	v_mul_f32_e32 v122, v36, v36
	v_mul_f32_e32 v124, v40, v40
	v_pk_fma_f32 v[62:63], v[118:119], v[118:119], v[120:121]
	v_pk_add_f32 v[56:57], v[60:61], v[56:57]
	v_pk_mul_f32 v[126:127], v[38:39], v[38:39]
	v_pk_mul_f32 v[128:129], v[42:43], v[42:43]
	v_pk_fma_f32 v[122:123], v[36:37], v[36:37], v[122:123] op_sel_hi:[1,1,0]
	v_pk_fma_f32 v[124:125], v[40:41], v[40:41], v[124:125] op_sel_hi:[1,1,0]
	v_pk_add_f32 v[62:63], v[62:63], v[62:63] op_sel_hi:[0,1]
	v_pk_add_f32 v[56:57], v[56:57], v[56:57] op_sel_hi:[0,1]
	v_mov_b32_e32 v122, v126
	v_mov_b32_e32 v124, v127
	v_mov_b32_e32 v62, v128
	v_mov_b32_e32 v56, v129
	v_pk_add_f32 v[106:107], v[122:123], v[124:125]
	v_pk_add_f32 v[56:57], v[62:63], v[56:57]
	v_pk_add_f32 v[78:79], v[78:79], 1.0 op_sel_hi:[1,0]
	v_pk_add_f32 v[56:57], v[106:107], v[56:57]
	v_pk_add_f32 v[76:77], v[76:77], 1.0 op_sel_hi:[1,0]
	v_add_f32_e32 v55, v56, v57
	ds_bpermute_b32 v56, v44, v55
	v_pk_add_f32 v[74:75], v[74:75], 1.0 op_sel_hi:[1,0]
	v_pk_add_f32 v[72:73], v[72:73], 1.0 op_sel_hi:[1,0]
	s_waitcnt lgkmcnt(0)
	v_add_f32_e32 v55, v55, v56
	ds_bpermute_b32 v56, v45, v55
	s_waitcnt lgkmcnt(0)
	v_add_f32_e32 v55, v55, v56
	ds_bpermute_b32 v56, v46, v55
	s_waitcnt lgkmcnt(0)
	v_add_f32_e32 v55, v55, v56
	ds_bpermute_b32 v56, v47, v55
	s_waitcnt lgkmcnt(0)
	v_add_f32_e32 v55, v55, v56
	ds_bpermute_b32 v56, v48, v55
	s_waitcnt lgkmcnt(0)
	v_add_f32_e32 v55, v55, v56
	ds_bpermute_b32 v56, v49, v55
	s_waitcnt lgkmcnt(0)
	v_add_f32_e32 v55, v55, v56
	v_fmamk_f32 v55, v55, 0x3a000000, v50
	v_rsq_f32_e32 v106, v55
	s_nop 0
	v_pk_mul_f32 v[56:57], v[84:85], v[106:107] op_sel_hi:[1,0]
	v_pk_mul_f32 v[58:59], v[82:83], v[106:107] op_sel_hi:[1,0]
	v_pk_mul_f32 v[60:61], v[88:89], v[106:107] op_sel_hi:[1,0]
	v_pk_mul_f32 v[62:63], v[86:87], v[106:107] op_sel_hi:[1,0]
	v_pk_mul_f32 v[58:59], v[6:7], v[58:59]
	v_pk_mul_f32 v[56:57], v[8:9], v[56:57]
	v_pk_mul_f32 v[62:63], v[2:3], v[62:63]
	v_pk_mul_f32 v[60:61], v[4:5], v[60:61]
	v_pk_fma_f32 v[70:71], v[78:79], v[56:57], v[70:71]
	v_pk_fma_f32 v[56:57], v[76:77], v[58:59], v[68:69]
	v_pk_fma_f32 v[60:61], v[74:75], v[60:61], v[66:67]
	v_pk_fma_f32 v[58:59], v[72:73], v[62:63], v[64:65]
	v_cvt_pk_bf16_f32 v56, v56, v57
	v_cvt_pk_bf16_f32 v57, v70, v71
	v_cvt_pk_bf16_f32 v58, v58, v59
	v_cvt_pk_bf16_f32 v59, v60, v61
	global_store_dwordx4 v[80:81], v[56:59], off sc1
	global_load_dwordx4 v[56:59], v52, s[8:9]
	s_nop 0
	global_load_dwordx4 v[60:63], v52, s[8:9] offset:16
	global_load_dwordx4 v[64:67], v52, s[6:7]
	global_load_dwordx4 v[68:71], v52, s[6:7] offset:16
	v_pk_mul_f32 v[74:75], v[92:93], v[106:107] op_sel_hi:[1,0]
	v_pk_mul_f32 v[76:77], v[90:91], v[106:107] op_sel_hi:[1,0]
	v_pk_mul_f32 v[78:79], v[96:97], v[106:107] op_sel_hi:[1,0]
	v_pk_mul_f32 v[80:81], v[94:95], v[106:107] op_sel_hi:[1,0]
	v_pk_mul_f32 v[76:77], v[14:15], v[76:77]
	v_pk_mul_f32 v[74:75], v[16:17], v[74:75]
	v_pk_mul_f32 v[80:81], v[10:11], v[80:81]
	v_pk_mul_f32 v[78:79], v[12:13], v[78:79]
	v_add_co_u32_e32 v72, vcc, s11, v34
	v_pk_mul_f32 v[40:41], v[40:41], v[106:107] op_sel_hi:[1,0]
	s_nop 0
	v_addc_co_u32_e32 v73, vcc, -1, v35, vcc
	v_pk_mul_f32 v[36:37], v[36:37], v[106:107] op_sel_hi:[1,0]
	v_pk_mul_f32 v[42:43], v[42:43], v[106:107] op_sel_hi:[1,0]
	v_pk_mul_f32 v[38:39], v[38:39], v[106:107] op_sel_hi:[1,0]
	v_pk_mul_f32 v[36:37], v[30:31], v[36:37]
	v_pk_mul_f32 v[40:41], v[32:33], v[40:41]
	v_pk_mul_f32 v[38:39], v[26:27], v[38:39]
	v_pk_mul_f32 v[42:43], v[28:29], v[42:43]
	v_lshl_add_u64 v[34:35], v[34:35], 0, s[0:1]
	s_waitcnt vmcnt(3)
	v_pk_add_f32 v[58:59], v[58:59], 1.0 op_sel_hi:[1,0]
	v_pk_add_f32 v[56:57], v[56:57], 1.0 op_sel_hi:[1,0]
	s_waitcnt vmcnt(2)
	v_pk_add_f32 v[62:63], v[62:63], 1.0 op_sel_hi:[1,0]
	v_pk_add_f32 v[60:61], v[60:61], 1.0 op_sel_hi:[1,0]
	s_waitcnt vmcnt(1)
	v_pk_fma_f32 v[58:59], v[58:59], v[74:75], v[66:67]
	v_pk_fma_f32 v[56:57], v[56:57], v[76:77], v[64:65]
	s_waitcnt vmcnt(0)
	v_pk_fma_f32 v[62:63], v[62:63], v[78:79], v[70:71]
	v_pk_fma_f32 v[60:61], v[60:61], v[80:81], v[68:69]
	v_cvt_pk_bf16_f32 v56, v56, v57
	v_cvt_pk_bf16_f32 v57, v58, v59
	v_cvt_pk_bf16_f32 v58, v60, v61
	v_cvt_pk_bf16_f32 v59, v62, v63
	global_store_dwordx4 v[72:73], v[56:59], off offset:-3072 sc1
	global_load_dwordx4 v[56:59], v53, s[8:9]
	s_nop 0
	global_load_dwordx4 v[60:63], v53, s[8:9] offset:16
	global_load_dwordx4 v[64:67], v53, s[6:7]
	global_load_dwordx4 v[68:71], v53, s[6:7] offset:16
	v_pk_mul_f32 v[74:75], v[100:101], v[106:107] op_sel_hi:[1,0]
	v_pk_mul_f32 v[76:77], v[98:99], v[106:107] op_sel_hi:[1,0]
	v_pk_mul_f32 v[78:79], v[104:105], v[106:107] op_sel_hi:[1,0]
	v_pk_mul_f32 v[80:81], v[102:103], v[106:107] op_sel_hi:[1,0]
	v_pk_mul_f32 v[76:77], v[22:23], v[76:77]
	v_pk_mul_f32 v[74:75], v[24:25], v[74:75]
	v_pk_mul_f32 v[80:81], v[18:19], v[80:81]
	v_pk_mul_f32 v[78:79], v[20:21], v[78:79]
	s_waitcnt vmcnt(3)
	v_pk_add_f32 v[58:59], v[58:59], 1.0 op_sel_hi:[1,0]
	v_pk_add_f32 v[56:57], v[56:57], 1.0 op_sel_hi:[1,0]
	s_waitcnt vmcnt(2)
	v_pk_add_f32 v[62:63], v[62:63], 1.0 op_sel_hi:[1,0]
	v_pk_add_f32 v[60:61], v[60:61], 1.0 op_sel_hi:[1,0]
	s_waitcnt vmcnt(1)
	v_pk_fma_f32 v[58:59], v[58:59], v[74:75], v[66:67]
	v_pk_fma_f32 v[56:57], v[56:57], v[76:77], v[64:65]
	s_waitcnt vmcnt(0)
	v_pk_fma_f32 v[62:63], v[62:63], v[78:79], v[70:71]
	v_pk_fma_f32 v[60:61], v[60:61], v[80:81], v[68:69]
	v_cvt_pk_bf16_f32 v56, v56, v57
	v_cvt_pk_bf16_f32 v57, v58, v59
	v_cvt_pk_bf16_f32 v58, v60, v61
	v_cvt_pk_bf16_f32 v59, v62, v63
	global_store_dwordx4 v[72:73], v[56:59], off offset:-2048 sc1
	global_load_dwordx4 v[56:59], v54, s[8:9]
	s_nop 0
	global_load_dwordx4 v[60:63], v54, s[8:9] offset:16
	global_load_dwordx4 v[64:67], v54, s[6:7]
	global_load_dwordx4 v[68:71], v54, s[6:7] offset:16
	s_waitcnt vmcnt(3)
	v_pk_add_f32 v[58:59], v[58:59], 1.0 op_sel_hi:[1,0]
	v_pk_add_f32 v[56:57], v[56:57], 1.0 op_sel_hi:[1,0]
	s_waitcnt vmcnt(2)
	v_pk_add_f32 v[62:63], v[62:63], 1.0 op_sel_hi:[1,0]
	v_pk_add_f32 v[60:61], v[60:61], 1.0 op_sel_hi:[1,0]
	s_waitcnt vmcnt(1)
	v_pk_fma_f32 v[40:41], v[58:59], v[40:41], v[66:67]
	v_pk_fma_f32 v[36:37], v[56:57], v[36:37], v[64:65]
	s_waitcnt vmcnt(0)
	v_pk_fma_f32 v[42:43], v[42:43], v[62:63], v[70:71]
	v_pk_fma_f32 v[38:39], v[38:39], v[60:61], v[68:69]
	v_cvt_pk_bf16_f32 v36, v36, v37
	v_cvt_pk_bf16_f32 v37, v40, v41
	v_cvt_pk_bf16_f32 v38, v38, v39
	v_cvt_pk_bf16_f32 v39, v42, v43
	global_store_dwordx4 v[72:73], v[36:39], off offset:-1024 sc1
	s_cbranch_scc1 .LBB0_921
.LBB0_922:
	v_readlane_b32 s0, v254, 0
	v_readlane_b32 s1, v254, 1
	s_cmp_gt_i32 s1, 10
	s_cselect_b64 s[0:1], -1, 0
	s_and_b64 s[4:5], s[4:5], s[0:1]
	s_andn2_b64 vcc, exec, s[4:5]
	s_cbranch_vccnz .LBB0_976
	s_waitcnt vmcnt(0)
	s_waitcnt vmcnt(0)
	s_barrier
	s_mov_b64 s[4:5], exec
	v_readlane_b32 s6, v254, 7
	v_readlane_b32 s7, v254, 8
	s_and_b64 s[6:7], s[4:5], s[6:7]
	s_mov_b64 exec, s[6:7]
	s_cbranch_execz .LBB0_975
	s_cmpk_lg_i32 s3, 0x100
	s_cbranch_scc1 .Lmy_gb9_orig
	s_and_b32 s6, s2, 7
	s_lshl_b32 s6, s6, 6
	s_add_u32 s6, s6, 0x34600
	v_mov_b32_e32 v2, s6
	v_mov_b32_e32 v3, 1
	global_atomic_add v2, v3, s[50:51]
	s_movk_i32 s7, 0x4000

.Lmy_gb9_go:
	s_movk_i32 s7, 0x4000
.Lmy_gb9_cspin:
	v_mov_b32_e32 v2, 0x35000
	global_load_dword v4, v2, s[50:51] offset:0 sc1
	global_load_dword v5, v2, s[50:51] offset:256 sc1
	global_load_dword v6, v2, s[50:51] offset:512 sc1
	global_load_dword v7, v2, s[50:51] offset:768 sc1
	global_load_dword v8, v2, s[50:51] offset:1024 sc1
	global_load_dword v9, v2, s[50:51] offset:1280 sc1
	global_load_dword v10, v2, s[50:51] offset:1536 sc1
	global_load_dword v11, v2, s[50:51] offset:1792 sc1
	global_load_dword v12, v2, s[50:51] offset:2048 sc1
	global_load_dword v13, v2, s[50:51] offset:2304 sc1
	global_load_dword v14, v2, s[50:51] offset:2560 sc1
	global_load_dword v15, v2, s[50:51] offset:2816 sc1
	global_load_dword v16, v2, s[50:51] offset:3072 sc1
	global_load_dword v17, v2, s[50:51] offset:3328 sc1
	global_load_dword v18, v2, s[50:51] offset:3584 sc1
	global_load_dword v19, v2, s[50:51] offset:3840 sc1
	s_waitcnt vmcnt(0)
	v_add_u32_e32 v4, v4, v5
	v_add_u32_e32 v4, v4, v6
	v_add_u32_e32 v4, v4, v7
	v_add_u32_e32 v4, v4, v8
	v_add_u32_e32 v4, v4, v9
	v_add_u32_e32 v4, v4, v10
	v_add_u32_e32 v4, v4, v11
	v_add_u32_e32 v4, v4, v12
	v_add_u32_e32 v4, v4, v13
	v_add_u32_e32 v4, v4, v14
	v_add_u32_e32 v4, v4, v15
	v_add_u32_e32 v4, v4, v16
	v_add_u32_e32 v4, v4, v17
	v_add_u32_e32 v4, v4, v18
	v_add_u32_e32 v4, v4, v19
	v_cmp_gt_u32_e32 vcc, 0x700, v4
	s_cbranch_vccz .Lmy_gb9_cgo
	s_sleep 1
	s_sub_u32 s7, s7, 1
	s_cmp_lg_u32 s7, 0
	s_cbranch_scc1 .Lmy_gb9_cspin

.Lmy_gb9_orig:
	s_add_i32 s6, 0, 0x23fc0
	v_mov_b32_e32 v2, s6
	s_waitcnt vmcnt(0) expcnt(0) lgkmcnt(0)
	ds_read_b32 v4, v2
	s_add_i32 s6, 0, 0x23fc4
	v_mov_b32_e32 v2, s6
	ds_read_b32 v2, v2
	s_waitcnt lgkmcnt(1)
	v_cmp_ne_u32_e32 vcc, 0, v4
	s_cbranch_vccnz .LBB0_939
	v_readlane_b32 s6, v254, 2
	v_readlane_b32 s7, v254, 3
	s_load_dwordx2 s[10:11], s[6:7], 0x4
	s_add_u32 s6, s50, 0x28200
	s_addc_u32 s7, s51, 0
	s_add_u32 s8, s50, 0x28400
	s_addc_u32 s9, s51, 0
	s_waitcnt lgkmcnt(0)
	s_mul_i32 s28, s10, s3
	s_add_u32 s10, s50, 0x28500
	s_mul_i32 s28, s28, s11
	s_addc_u32 s11, s51, 0
	s_add_u32 s12, s50, 0x28600
	s_addc_u32 s13, s51, 0
	s_add_u32 s14, s50, 0x28700
	s_addc_u32 s15, s51, 0
	s_add_u32 s16, s50, 0x28800
	s_addc_u32 s17, s51, 0
	s_add_u32 s18, s50, 0x28900
	s_addc_u32 s19, s51, 0
	s_add_u32 s20, s50, 0x28a00
	s_addc_u32 s21, s51, 0
	s_add_u32 s22, s50, 0x28b00
	s_addc_u32 s23, s51, 0
	s_add_u32 s24, s50, 0x28c00
	s_addc_u32 s25, s51, 0
	s_add_u32 s26, s50, 0x28d00
	s_addc_u32 s27, s51, 0
	s_add_u32 s36, s50, 0x28e00
	s_addc_u32 s37, s51, 0
	s_add_u32 s40, s50, 0x28f00
	s_addc_u32 s41, s51, 0
	s_add_u32 s42, s50, 0x29000
	s_addc_u32 s43, s51, 0
	s_add_u32 s44, s50, 0x29100
	s_addc_u32 s45, s51, 0
	s_add_u32 s52, s50, 0x29200
	s_addc_u32 s53, s51, 0
	s_add_u32 s54, s50, 0x29300
	s_addc_u32 s55, s51, 0
	s_mov_b32 s29, 1
	v_mov_b32_e32 v18, 0
	s_branch .LBB0_927
